# diff attention tile loop: per-segment s_setprio flips replaced by one static s_setprio 1 for waves 4-7 per unit
# baseline (speedup 1.0000x reference)
.LBB0_472:
	s_or_b64 exec, exec, s[0:1]
	s_waitcnt vmcnt(5)
	v_lshlrev_b32_e32 v35, 16, v30
	v_and_b32_e32 v30, 0xffff0000, v30
	v_mul_f32_e32 v30, 0x3e38aa3b, v30
	v_mul_f32_e32 v35, 0x3e38aa3b, v35
	v_cvt_pk_bf16_f32 v98, v35, v30
	v_lshlrev_b32_e32 v30, 16, v31
	v_mul_f32_e32 v30, 0x3e38aa3b, v30
	v_and_b32_e32 v31, 0xffff0000, v31
	v_mul_f32_e32 v31, 0x3e38aa3b, v31
	v_cvt_pk_bf16_f32 v99, v30, v31
	v_lshlrev_b32_e32 v30, 16, v32
	v_mul_f32_e32 v30, 0x3e38aa3b, v30
	v_and_b32_e32 v31, 0xffff0000, v32
	v_mul_f32_e32 v31, 0x3e38aa3b, v31
	v_cvt_pk_bf16_f32 v100, v30, v31
	v_lshlrev_b32_e32 v30, 16, v33
	v_mul_f32_e32 v30, 0x3e38aa3b, v30
	v_and_b32_e32 v31, 0xffff0000, v33
	v_mul_f32_e32 v31, 0x3e38aa3b, v31
	v_cvt_pk_bf16_f32 v101, v30, v31
	s_waitcnt vmcnt(3)
	v_lshlrev_b32_e32 v30, 16, v26
	v_and_b32_e32 v26, 0xffff0000, v26
	v_mul_f32_e32 v26, 0x3e38aa3b, v26
	v_mul_f32_e32 v30, 0x3e38aa3b, v30
	v_cvt_pk_bf16_f32 v102, v30, v26
	v_lshlrev_b32_e32 v26, 16, v27
	v_mul_f32_e32 v26, 0x3e38aa3b, v26
	v_and_b32_e32 v27, 0xffff0000, v27
	v_mul_f32_e32 v27, 0x3e38aa3b, v27
	v_cvt_pk_bf16_f32 v103, v26, v27
	v_lshlrev_b32_e32 v26, 16, v28
	v_mul_f32_e32 v26, 0x3e38aa3b, v26
	v_and_b32_e32 v27, 0xffff0000, v28
	v_mul_f32_e32 v27, 0x3e38aa3b, v27
	v_cvt_pk_bf16_f32 v104, v26, v27
	v_lshlrev_b32_e32 v26, 16, v29
	v_mul_f32_e32 v26, 0x3e38aa3b, v26
	v_and_b32_e32 v27, 0xffff0000, v29
	v_mul_f32_e32 v27, 0x3e38aa3b, v27
	v_cvt_pk_bf16_f32 v105, v26, v27
	v_lshlrev_b32_e32 v26, 16, v22
	v_and_b32_e32 v22, 0xffff0000, v22
	v_mul_f32_e32 v22, 0x3e38aa3b, v22
	v_mul_f32_e32 v26, 0x3e38aa3b, v26
	v_cvt_pk_bf16_f32 v106, v26, v22
	v_lshlrev_b32_e32 v22, 16, v23
	v_mul_f32_e32 v22, 0x3e38aa3b, v22
	v_and_b32_e32 v23, 0xffff0000, v23
	v_mul_f32_e32 v23, 0x3e38aa3b, v23
	v_cvt_pk_bf16_f32 v107, v22, v23
	v_lshlrev_b32_e32 v22, 16, v24
	v_mul_f32_e32 v22, 0x3e38aa3b, v22
	v_and_b32_e32 v23, 0xffff0000, v24
	v_mul_f32_e32 v23, 0x3e38aa3b, v23
	v_cvt_pk_bf16_f32 v108, v22, v23
	v_lshlrev_b32_e32 v22, 16, v25
	v_mul_f32_e32 v22, 0x3e38aa3b, v22
	v_and_b32_e32 v23, 0xffff0000, v25
	v_mul_f32_e32 v23, 0x3e38aa3b, v23
	v_cvt_pk_bf16_f32 v109, v22, v23
	v_lshlrev_b32_e32 v22, 16, v14
	v_and_b32_e32 v14, 0xffff0000, v14
	v_mul_f32_e32 v14, 0x3e38aa3b, v14
	v_mul_f32_e32 v22, 0x3e38aa3b, v22
	v_cvt_pk_bf16_f32 v110, v22, v14
	v_lshlrev_b32_e32 v14, 16, v15
	v_mul_f32_e32 v14, 0x3e38aa3b, v14
	v_and_b32_e32 v15, 0xffff0000, v15
	v_mul_f32_e32 v15, 0x3e38aa3b, v15
	v_cvt_pk_bf16_f32 v111, v14, v15
	v_lshlrev_b32_e32 v14, 16, v16
	v_mul_f32_e32 v14, 0x3e38aa3b, v14
	v_and_b32_e32 v15, 0xffff0000, v16
	v_mul_f32_e32 v15, 0x3e38aa3b, v15
	v_cvt_pk_bf16_f32 v112, v14, v15
	v_lshlrev_b32_e32 v14, 16, v17
	v_mul_f32_e32 v14, 0x3e38aa3b, v14
	v_and_b32_e32 v15, 0xffff0000, v17
	s_movk_i32 s0, 0x110
	v_mul_f32_e32 v15, 0x3e38aa3b, v15
	v_cvt_pk_bf16_f32 v113, v14, v15
	v_mul_lo_u32 v14, v37, s0
	v_lshl_add_u32 v151, v38, 4, v14
	s_movk_i32 s0, 0x90
	v_mul_lo_u32 v14, v36, s0
	v_lshlrev_b32_e32 v16, 3, v134
	v_add_u32_e32 v17, 0, v151
	v_and_b32_e32 v15, 0x60, v34
	ds_write_b128 v17, v[6:9]
	s_waitcnt vmcnt(1)
	ds_write_b128 v17, v[18:21] offset:8704
	v_and_or_b32 v6, v16, 8, v14
	v_add_u32_e32 v152, v6, v15
	v_add_u32_e32 v6, 0, v152
	v_add_u32_e32 v7, 0x4000, v6
	ds_write2_b64 v7, v[2:3], v[4:5] offset0:128 offset1:130
	v_add_u32_e32 v2, 0x6800, v6
	v_readlane_b32 s0, v253, 49
	s_waitcnt vmcnt(0)
	ds_write2_b64 v2, v[10:11], v[12:13] offset1:2
	s_waitcnt lgkmcnt(0)
	v_mov_b32_e32 v2, s0
	s_barrier
	ds_read_b32 v149, v2
	v_mov_b32_e32 v137, 1.0
	v_mov_b32_e32 v17, 0
	s_cmp_lt_i32 s2, 0
	v_mov_b32_e32 v16, 0
	v_mov_b32_e32 v15, 0
	v_mov_b32_e32 v14, 0
	v_mov_b32_e32 v13, 0
	v_mov_b32_e32 v12, 0
	v_mov_b32_e32 v11, 0
	v_mov_b32_e32 v10, 0
	v_mov_b32_e32 v9, 0
	v_mov_b32_e32 v8, 0
	v_mov_b32_e32 v7, 0
	v_mov_b32_e32 v6, 0
	v_mov_b32_e32 v5, 0
	v_mov_b32_e32 v4, 0
	v_mov_b32_e32 v3, 0
	v_mov_b32_e32 v2, 0
	v_mov_b32_e32 v33, 0
	v_mov_b32_e32 v32, 0
	v_mov_b32_e32 v31, 0
	v_mov_b32_e32 v30, 0
	v_mov_b32_e32 v29, 0
	v_mov_b32_e32 v28, 0
	v_mov_b32_e32 v27, 0
	v_mov_b32_e32 v26, 0
	v_mov_b32_e32 v25, 0
	v_mov_b32_e32 v24, 0
	v_mov_b32_e32 v23, 0
	v_mov_b32_e32 v22, 0
	v_mov_b32_e32 v21, 0
	v_mov_b32_e32 v20, 0
	v_mov_b32_e32 v19, 0
	v_mov_b32_e32 v18, 0
	v_mov_b32_e32 v49, 0
	v_mov_b32_e32 v48, 0
	v_mov_b32_e32 v47, 0
	v_mov_b32_e32 v46, 0
	v_mov_b32_e32 v45, 0
	v_mov_b32_e32 v44, 0
	v_mov_b32_e32 v43, 0
	v_mov_b32_e32 v42, 0
	v_mov_b32_e32 v41, 0
	v_mov_b32_e32 v40, 0
	v_mov_b32_e32 v39, 0
	v_mov_b32_e32 v38, 0
	v_mov_b32_e32 v37, 0
	v_mov_b32_e32 v36, 0
	v_mov_b32_e32 v35, 0
	v_mov_b32_e32 v34, 0
	v_mov_b32_e32 v65, 0
	v_mov_b32_e32 v64, 0
	v_mov_b32_e32 v63, 0
	v_mov_b32_e32 v62, 0
	v_mov_b32_e32 v61, 0
	v_mov_b32_e32 v60, 0
	v_mov_b32_e32 v59, 0
	v_mov_b32_e32 v58, 0
	v_mov_b32_e32 v57, 0
	v_mov_b32_e32 v56, 0
	v_mov_b32_e32 v55, 0
	v_mov_b32_e32 v54, 0
	v_mov_b32_e32 v53, 0
	v_mov_b32_e32 v52, 0
	v_mov_b32_e32 v51, 0
	v_mov_b32_e32 v50, 0
	v_mov_b32_e32 v131, 0
	s_cbranch_scc1 .LBB0_492
	s_movk_i32 s0, 0x1c00
	v_mad_i64_i32 v[2:3], s[0:1], v70, s0, 0
	v_lshl_add_u64 v[2:3], v[2:3], 0, v[0:1]
	v_mov_b32_e32 v14, v1
	v_mov_b32_e32 v15, v1
	s_mov_b64 s[0:1], 0x1800
	v_lshl_add_u64 v[144:145], s[42:43], 0, v[2:3]
	v_mov_b32_e32 v0, v1
	v_mov_b32_e32 v2, v1
	v_mov_b32_e32 v3, v1
	v_mov_b32_e32 v4, v1
	v_mov_b32_e32 v5, v1
	v_mov_b32_e32 v6, v1
	v_mov_b32_e32 v7, v1
	v_mov_b32_e32 v8, v1
	v_mov_b32_e32 v9, v1
	v_mov_b32_e32 v10, v1
	v_mov_b32_e32 v11, v1
	v_mov_b32_e32 v12, v1
	v_mov_b32_e32 v13, v1
	v_mov_b64_e32 v[64:65], v[14:15]
	v_mov_b64_e32 v[48:49], v[14:15]
	v_mov_b64_e32 v[32:33], v[14:15]
	v_lshl_add_u64 v[140:141], v[66:67], 0, s[0:1]
	s_mov_b64 s[0:1], 0x200000
	s_lshl_b32 s2, s2, 1
	v_ashrrev_i32_e32 v155, 8, v134
	v_subrev_u32_e32 v156, 63, v69
	v_mov_b64_e32 v[62:63], v[12:13]
	v_mov_b64_e32 v[60:61], v[10:11]
	v_mov_b64_e32 v[58:59], v[8:9]
	v_mov_b64_e32 v[56:57], v[6:7]
	v_mov_b64_e32 v[54:55], v[4:5]
	v_mov_b64_e32 v[52:53], v[2:3]
	v_mov_b64_e32 v[50:51], v[0:1]
	v_mov_b64_e32 v[46:47], v[12:13]
	v_mov_b64_e32 v[44:45], v[10:11]
	v_mov_b64_e32 v[42:43], v[8:9]
	v_mov_b64_e32 v[40:41], v[6:7]
	v_mov_b64_e32 v[38:39], v[4:5]
	v_mov_b64_e32 v[36:37], v[2:3]
	v_mov_b64_e32 v[34:35], v[0:1]
	v_mov_b64_e32 v[30:31], v[12:13]
	v_mov_b64_e32 v[28:29], v[10:11]
	v_mov_b64_e32 v[26:27], v[8:9]
	v_mov_b64_e32 v[24:25], v[6:7]
	v_mov_b64_e32 v[22:23], v[4:5]
	v_mov_b64_e32 v[20:21], v[2:3]
	v_mov_b64_e32 v[18:19], v[0:1]
	v_mov_b64_e32 v[16:17], v[14:15]
	v_lshl_add_u64 v[142:143], v[138:139], 0, s[0:1]
	v_add_u32_e32 v157, s2, v155
	v_mul_u32_u24_e32 v154, 0x110, v68
	v_mul_i32_i24_e32 v153, -4, v135
	v_mul_u32_u24_e32 v133, 0x90, v68
	v_mad_i32_i24 v158, v135, -4, v68
	s_or_b32 s3, s2, 1
	s_mov_b32 s4, 0
	v_mov_b32_e32 v150, 0xff800000
	v_mov_b32_e32 v131, 0
	s_mov_b32 s52, 64
	v_mov_b32_e32 v159, v156
	v_mov_b64_e32 v[14:15], v[12:13]
	v_mov_b64_e32 v[12:13], v[10:11]
	v_mov_b64_e32 v[10:11], v[8:9]
	v_mov_b64_e32 v[8:9], v[6:7]
	v_mov_b64_e32 v[6:7], v[4:5]
	v_mov_b64_e32 v[4:5], v[2:3]
	v_mov_b64_e32 v[2:3], v[0:1]
	v_readfirstlane_b32 s0, v147
	s_cmp_lt_u32 s0, 2
	s_cbranch_scc1 .Ldf_noprio
	s_setprio 1
.Ldf_noprio:
	s_branch .LBB0_475
.LBB0_474:
	s_add_i32 s4, s4, 1
	s_add_i32 s52, s52, 64
	s_mov_b64 s[0:1], 0x70000
	v_subrev_u32_e32 v159, 64, v159
	s_cmp_eq_u32 s3, s4
	v_lshl_add_u64 v[144:145], v[144:145], 0, s[0:1]
	s_waitcnt lgkmcnt(0)
	s_barrier
	s_cbranch_scc1 .LBB0_485

.LBB0_479:
	s_bitcmp1_b32 s4, 0
	s_cselect_b32 s0, 0x8c00, 0
	s_add_i32 s5, s0, 0
	v_add_u32_e32 v0, s5, v154
	v_add3_u32 v0, v0, v136, v130
	ds_read_b128 v[66:69], v0
	ds_read_b128 v[170:173], v0 offset:32
	ds_read_b128 v[70:73], v0 offset:8704
	ds_read_b128 v[174:177], v0 offset:8736
	ds_read_b128 v[178:181], v0 offset:64
	ds_read_b128 v[182:185], v0 offset:96
	ds_read_b128 v[186:189], v0 offset:8768
	ds_read_b128 v[190:193], v0 offset:8800
	s_movk_i32 s0, 0x7f
	v_cmp_lt_i32_e32 vcc, s0, v159
	v_cmp_gt_i32_e64 s[40:41], s21, v159
	s_waitcnt lgkmcnt(7)
	v_mfma_f32_32x32x16_bf16 v[82:97], v[66:69], v[98:101], 0
	s_waitcnt lgkmcnt(5)
	v_mfma_f32_32x32x16_bf16 v[66:81], v[70:73], v[98:101], 0
	v_mfma_f32_32x32x16_bf16 v[82:97], v[170:173], v[102:105], v[82:97]
	s_waitcnt lgkmcnt(4)
	v_mfma_f32_32x32x16_bf16 v[66:81], v[174:177], v[102:105], v[66:81]
	s_waitcnt lgkmcnt(3)
	v_mfma_f32_32x32x16_bf16 v[82:97], v[178:181], v[106:109], v[82:97]
	s_waitcnt lgkmcnt(1)
	v_mfma_f32_32x32x16_bf16 v[66:81], v[186:189], v[106:109], v[66:81]
	v_mfma_f32_32x32x16_bf16 v[82:97], v[182:185], v[110:113], v[82:97]
	s_waitcnt lgkmcnt(0)
	v_mfma_f32_32x32x16_bf16 v[66:81], v[190:193], v[110:113], v[66:81]
	s_and_saveexec_b64 s[0:1], s[40:41]
	s_cbranch_execz .LBB0_481
	v_add_u32_e32 v0, v158, v159
	v_add_u32_e32 v170, 63, v0
	s_movk_i32 s12, 0xffc0
	s_movk_i32 s11, 0xffe0
	v_med3_i32 v171, v170, s12, v214
	v_med3_i32 v170, v170, s11, v215
	v_lshl_add_u32 v172, v170, 2, s33
	v_add_u32_e32 v170, 62, v0
	v_med3_i32 v173, v170, s12, v214
	v_med3_i32 v170, v170, s11, v215
	v_lshl_add_u32 v174, v170, 2, s33
	v_add_u32_e32 v170, 61, v0
	v_med3_i32 v175, v170, s12, v214
	v_med3_i32 v170, v170, s11, v215
	v_lshl_add_u32 v176, v170, 2, s33
	v_add_u32_e32 v170, 60, v0
	v_med3_i32 v177, v170, s12, v214
	v_med3_i32 v170, v170, s11, v215
	v_lshl_add_u32 v171, v171, 2, s33
	v_lshl_add_u32 v173, v173, 2, s33
	v_lshl_add_u32 v175, v175, 2, s33
	v_lshl_add_u32 v177, v177, 2, s33
	v_lshl_add_u32 v178, v170, 2, s33
	ds_read_b32 v170, v171 offset:256
	ds_read_b32 v172, v172 offset:128
	ds_read_b32 v171, v173 offset:256
	ds_read_b32 v173, v174 offset:128
	ds_read_b32 v174, v175 offset:256
	ds_read_b32 v176, v176 offset:128
	ds_read_b32 v175, v177 offset:256
	ds_read_b32 v177, v178 offset:128
	v_add_u32_e32 v178, 55, v0
	v_med3_i32 v179, v178, s12, v214
	v_med3_i32 v178, v178, s11, v215
	v_lshl_add_u32 v180, v178, 2, s33
	v_add_u32_e32 v178, 54, v0
	v_med3_i32 v181, v178, s12, v214
	v_med3_i32 v178, v178, s11, v215
	v_lshl_add_u32 v182, v178, 2, s33
	v_add_u32_e32 v178, 53, v0
	v_med3_i32 v183, v178, s12, v214
	v_med3_i32 v178, v178, s11, v215
	v_lshl_add_u32 v184, v178, 2, s33
	v_add_u32_e32 v178, 52, v0
	v_med3_i32 v185, v178, s12, v214
	v_med3_i32 v178, v178, s11, v215
	v_lshl_add_u32 v179, v179, 2, s33
	v_lshl_add_u32 v181, v181, 2, s33
	v_lshl_add_u32 v183, v183, 2, s33
	v_lshl_add_u32 v185, v185, 2, s33
	v_lshl_add_u32 v186, v178, 2, s33
	ds_read_b32 v178, v179 offset:256
	ds_read_b32 v180, v180 offset:128
	ds_read_b32 v179, v181 offset:256
	ds_read_b32 v181, v182 offset:128
	ds_read_b32 v182, v183 offset:256
	ds_read_b32 v184, v184 offset:128
	ds_read_b32 v183, v185 offset:256
	ds_read_b32 v185, v186 offset:128
	v_add_u32_e32 v186, 47, v0
	v_med3_i32 v187, v186, s12, v214
	v_med3_i32 v186, v186, s11, v215
	v_lshl_add_u32 v188, v186, 2, s33
	v_add_u32_e32 v186, 46, v0
	v_med3_i32 v189, v186, s12, v214
	v_med3_i32 v186, v186, s11, v215
	v_lshl_add_u32 v190, v186, 2, s33
	v_add_u32_e32 v186, 45, v0
	v_med3_i32 v191, v186, s12, v214
	v_med3_i32 v186, v186, s11, v215
	v_lshl_add_u32 v192, v186, 2, s33
	v_add_u32_e32 v186, 44, v0
	v_med3_i32 v193, v186, s12, v214
	v_med3_i32 v186, v186, s11, v215
	v_lshl_add_u32 v187, v187, 2, s33
	v_lshl_add_u32 v189, v189, 2, s33
	v_lshl_add_u32 v191, v191, 2, s33
	v_lshl_add_u32 v193, v193, 2, s33
	v_lshl_add_u32 v194, v186, 2, s33
	ds_read_b32 v186, v187 offset:256
	ds_read_b32 v188, v188 offset:128
	ds_read_b32 v187, v189 offset:256
	ds_read_b32 v189, v190 offset:128
	ds_read_b32 v190, v191 offset:256
	ds_read_b32 v192, v192 offset:128
	ds_read_b32 v191, v193 offset:256
	ds_read_b32 v193, v194 offset:128
	v_add_u32_e32 v194, 39, v0
	v_med3_i32 v195, v194, s12, v214
	v_med3_i32 v194, v194, s11, v215
	v_lshl_add_u32 v196, v194, 2, s33
	v_add_u32_e32 v194, 38, v0
	v_med3_i32 v197, v194, s12, v214
	v_med3_i32 v194, v194, s11, v215
	v_lshl_add_u32 v202, v194, 2, s33
	v_add_u32_e32 v194, 37, v0
	v_med3_i32 v198, v194, s12, v214
	v_med3_i32 v194, v194, s11, v215
	v_add_u32_e32 v0, 36, v0
	v_lshl_add_u32 v200, v194, 2, s33
	v_med3_i32 v194, v0, s12, v214
	v_lshl_add_u32 v195, v195, 2, s33
	v_lshl_add_u32 v197, v197, 2, s33
	v_lshl_add_u32 v198, v198, 2, s33
	v_lshl_add_u32 v199, v194, 2, s33
	v_med3_i32 v0, v0, s11, v215
	v_lshl_add_u32 v0, v0, 2, s33
	ds_read_b32 v194, v195 offset:256
	ds_read_b32 v196, v196 offset:128
	ds_read_b32 v198, v198 offset:256
	ds_read_b32 v199, v199 offset:256
	ds_read_b32 v195, v197 offset:256
	ds_read_b32 v201, v0 offset:128
	ds_read_b32 v200, v200 offset:128
	ds_read_b32 v197, v202 offset:128
	s_waitcnt lgkmcnt(4)
	v_pk_add_f32 v[96:97], v[96:97], v[198:199]
	s_waitcnt lgkmcnt(3)
	v_pk_add_f32 v[94:95], v[94:95], v[194:195]
	v_pk_add_f32 v[92:93], v[92:93], v[190:191]
	v_pk_add_f32 v[90:91], v[90:91], v[186:187]
	v_pk_add_f32 v[88:89], v[88:89], v[182:183]
	v_pk_add_f32 v[86:87], v[86:87], v[178:179]
	v_pk_add_f32 v[84:85], v[84:85], v[174:175]
	v_pk_add_f32 v[82:83], v[82:83], v[170:171]
	s_waitcnt lgkmcnt(1)
	v_pk_add_f32 v[80:81], v[80:81], v[200:201]
	s_waitcnt lgkmcnt(0)
	v_pk_add_f32 v[78:79], v[78:79], v[196:197]
	v_pk_add_f32 v[76:77], v[76:77], v[192:193]
	v_pk_add_f32 v[74:75], v[74:75], v[188:189]
	v_pk_add_f32 v[72:73], v[72:73], v[184:185]
	v_pk_add_f32 v[70:71], v[70:71], v[180:181]
	v_pk_add_f32 v[68:69], v[68:69], v[176:177]
	v_pk_add_f32 v[66:67], v[66:67], v[172:173]

.LBB0_483:
	v_sub_f32_e32 v0, v150, v0
	v_add3_u32 v203, s5, v133, v130
	ds_read_b128 v[224:227], v203 offset:17408
	ds_read_b128 v[228:231], v203 offset:22016
	ds_read_b128 v[232:235], v203 offset:26624
	ds_read_b128 v[236:239], v203 offset:31232
	ds_read_b128 v[240:243], v203 offset:17440
	ds_read_b128 v[244:247], v203 offset:22048
	ds_read_b128 v[248:251], v203 offset:26656
	ds_read_b128 v[204:207], v203 offset:31264
	v_pk_add_f32 v[82:83], v[82:83], v[0:1] op_sel_hi:[1,0] neg_lo:[0,1] neg_hi:[0,1]
	v_pk_add_f32 v[84:85], v[84:85], v[0:1] op_sel_hi:[1,0] neg_lo:[0,1] neg_hi:[0,1]
	v_exp_f32_e32 v82, v82
	v_exp_f32_e32 v83, v83
	v_pk_add_f32 v[86:87], v[86:87], v[0:1] op_sel_hi:[1,0] neg_lo:[0,1] neg_hi:[0,1]
	v_pk_add_f32 v[88:89], v[88:89], v[0:1] op_sel_hi:[1,0] neg_lo:[0,1] neg_hi:[0,1]
	v_exp_f32_e32 v84, v84
	v_exp_f32_e32 v85, v85
	v_exp_f32_e32 v86, v86
	v_exp_f32_e32 v87, v87
	v_exp_f32_e32 v88, v88
	v_exp_f32_e32 v89, v89
	v_cvt_pk_bf16_f32 v170, v82, v83
	v_cvt_pk_bf16_f32 v171, v84, v85
	v_cvt_pk_bf16_f32 v172, v86, v87
	v_cvt_pk_bf16_f32 v173, v88, v89
	v_pk_add_f32 v[186:187], v[82:83], v[84:85]
	v_pk_add_f32 v[186:187], v[186:187], v[86:87]
	v_pk_add_f32 v[186:187], v[186:187], v[88:89]
	s_waitcnt lgkmcnt(4)
	v_mfma_f32_32x32x16_bf16 v[50:65], v[224:227], v[170:173], v[50:65]
	v_pk_add_f32 v[90:91], v[90:91], v[0:1] op_sel_hi:[1,0] neg_lo:[0,1] neg_hi:[0,1]
	v_pk_add_f32 v[92:93], v[92:93], v[0:1] op_sel_hi:[1,0] neg_lo:[0,1] neg_hi:[0,1]
	v_exp_f32_e32 v90, v90
	v_exp_f32_e32 v91, v91
	v_mfma_f32_32x32x16_bf16 v[34:49], v[228:231], v[170:173], v[34:49]
	v_pk_add_f32 v[94:95], v[94:95], v[0:1] op_sel_hi:[1,0] neg_lo:[0,1] neg_hi:[0,1]
	v_pk_add_f32 v[96:97], v[96:97], v[0:1] op_sel_hi:[1,0] neg_lo:[0,1] neg_hi:[0,1]
	v_exp_f32_e32 v92, v92
	v_exp_f32_e32 v93, v93
	v_mfma_f32_32x32x16_bf16 v[18:33], v[232:235], v[170:173], v[18:33]
	v_exp_f32_e32 v94, v94
	v_exp_f32_e32 v95, v95
	v_exp_f32_e32 v96, v96
	v_exp_f32_e32 v97, v97
	v_cvt_pk_bf16_f32 v174, v90, v91
	v_cvt_pk_bf16_f32 v175, v92, v93
	v_mfma_f32_32x32x16_bf16 v[2:17], v[236:239], v[170:173], v[2:17]
	ds_read_b128 v[224:227], v203 offset:17472
	ds_read_b128 v[228:231], v203 offset:22080
	ds_read_b128 v[232:235], v203 offset:26688
	ds_read_b128 v[236:239], v203 offset:31296
	v_cvt_pk_bf16_f32 v176, v94, v95
	v_cvt_pk_bf16_f32 v177, v96, v97
	v_pk_add_f32 v[186:187], v[186:187], v[90:91]
	v_pk_add_f32 v[186:187], v[186:187], v[92:93]
	v_pk_add_f32 v[186:187], v[186:187], v[94:95]
	v_pk_add_f32 v[186:187], v[186:187], v[96:97]
	s_waitcnt lgkmcnt(4)
	v_mfma_f32_32x32x16_bf16 v[50:65], v[240:243], v[174:177], v[50:65]
	v_pk_add_f32 v[66:67], v[66:67], v[0:1] op_sel_hi:[1,0] neg_lo:[0,1] neg_hi:[0,1]
	v_pk_add_f32 v[68:69], v[68:69], v[0:1] op_sel_hi:[1,0] neg_lo:[0,1] neg_hi:[0,1]
	v_exp_f32_e32 v66, v66
	v_exp_f32_e32 v67, v67
	v_mfma_f32_32x32x16_bf16 v[34:49], v[244:247], v[174:177], v[34:49]
	v_pk_add_f32 v[70:71], v[70:71], v[0:1] op_sel_hi:[1,0] neg_lo:[0,1] neg_hi:[0,1]
	v_pk_add_f32 v[72:73], v[72:73], v[0:1] op_sel_hi:[1,0] neg_lo:[0,1] neg_hi:[0,1]
	v_exp_f32_e32 v68, v68
	v_exp_f32_e32 v69, v69
	v_mfma_f32_32x32x16_bf16 v[18:33], v[248:251], v[174:177], v[18:33]
	v_exp_f32_e32 v70, v70
	v_exp_f32_e32 v71, v71
	v_exp_f32_e32 v72, v72
	v_exp_f32_e32 v73, v73
	v_cvt_pk_bf16_f32 v178, v66, v67
	v_cvt_pk_bf16_f32 v179, v68, v69
	v_mfma_f32_32x32x16_bf16 v[2:17], v[204:207], v[174:177], v[2:17]
	ds_read_b128 v[240:243], v203 offset:17504
	ds_read_b128 v[244:247], v203 offset:22112
	ds_read_b128 v[248:251], v203 offset:26720
	ds_read_b128 v[204:207], v203 offset:31328
	v_cvt_pk_bf16_f32 v180, v70, v71
	v_cvt_pk_bf16_f32 v181, v72, v73
	v_pk_add_f32 v[186:187], v[186:187], v[66:67]
	v_pk_add_f32 v[186:187], v[186:187], v[68:69]
	v_pk_add_f32 v[186:187], v[186:187], v[70:71]
	v_pk_add_f32 v[186:187], v[186:187], v[72:73]
	s_waitcnt lgkmcnt(4)
	v_mfma_f32_32x32x16_bf16 v[50:65], v[224:227], v[178:181], v[50:65]
	v_pk_add_f32 v[74:75], v[74:75], v[0:1] op_sel_hi:[1,0] neg_lo:[0,1] neg_hi:[0,1]
	v_pk_add_f32 v[76:77], v[76:77], v[0:1] op_sel_hi:[1,0] neg_lo:[0,1] neg_hi:[0,1]
	v_exp_f32_e32 v74, v74
	v_exp_f32_e32 v75, v75
	v_mfma_f32_32x32x16_bf16 v[34:49], v[228:231], v[178:181], v[34:49]
	v_pk_add_f32 v[78:79], v[78:79], v[0:1] op_sel_hi:[1,0] neg_lo:[0,1] neg_hi:[0,1]
	v_pk_add_f32 v[80:81], v[80:81], v[0:1] op_sel_hi:[1,0] neg_lo:[0,1] neg_hi:[0,1]
	v_exp_f32_e32 v76, v76
	v_exp_f32_e32 v77, v77
	v_mfma_f32_32x32x16_bf16 v[18:33], v[232:235], v[178:181], v[18:33]
	v_exp_f32_e32 v78, v78
	v_exp_f32_e32 v79, v79
	v_exp_f32_e32 v80, v80
	v_exp_f32_e32 v81, v81
	v_cvt_pk_bf16_f32 v182, v74, v75
	v_cvt_pk_bf16_f32 v183, v76, v77
	v_mfma_f32_32x32x16_bf16 v[2:17], v[236:239], v[178:181], v[2:17]
	v_cvt_pk_bf16_f32 v184, v78, v79
	v_cvt_pk_bf16_f32 v185, v80, v81
	v_pk_add_f32 v[186:187], v[186:187], v[74:75]
	v_pk_add_f32 v[186:187], v[186:187], v[76:77]
	v_pk_add_f32 v[186:187], v[186:187], v[78:79]
	v_pk_add_f32 v[186:187], v[186:187], v[80:81]
	s_waitcnt lgkmcnt(0)
	v_mfma_f32_32x32x16_bf16 v[50:65], v[240:243], v[182:185], v[50:65]
	v_mfma_f32_32x32x16_bf16 v[34:49], v[244:247], v[182:185], v[34:49]
	v_mfma_f32_32x32x16_bf16 v[18:33], v[248:251], v[182:185], v[18:33]
	v_mfma_f32_32x32x16_bf16 v[2:17], v[204:207], v[182:185], v[2:17]
	v_add_f32_e32 v186, v186, v187
	v_add_f32_e32 v131, v131, v186
	s_or_b64 exec, exec, s[64:65]
	s_andn2_b64 vcc, exec, s[62:63]
	s_cbranch_vccnz .LBB0_474

.LBB0_485:
	v_cmp_lt_i32_e32 vcc, 0, v155
	s_and_saveexec_b64 s[62:63], vcc
	s_cbranch_execz .LBB0_491
	s_bitcmp1_b32 s3, 0
	s_cselect_b32 s0, 0x8c00, 0
	s_lshl_b32 s3, s3, 6
	s_add_i32 s2, s0, 0
	v_subrev_u32_e32 v0, s3, v156
	s_movk_i32 s0, 0x7f
	v_cmp_lt_i32_e32 vcc, s0, v0
	v_cmp_gt_i32_e64 s[40:41], s21, v0
	v_add_u32_e32 v0, s2, v154
	v_add3_u32 v0, v0, v136, v130
	ds_read_b128 v[66:69], v0 offset:8704
	ds_read_b128 v[70:73], v0
	s_waitcnt vmcnt(3)
	ds_read_b128 v[114:117], v0 offset:32
	s_waitcnt vmcnt(2)
	ds_read_b128 v[118:121], v0 offset:8736
	s_waitcnt vmcnt(1)
	ds_read_b128 v[122:125], v0 offset:64
	s_waitcnt vmcnt(0)
	ds_read_b128 v[126:129], v0 offset:8768
	ds_read_b128 v[138:141], v0 offset:96
	ds_read_b128 v[142:145], v0 offset:8800
	s_waitcnt lgkmcnt(6)
	v_mfma_f32_32x32x16_bf16 v[82:97], v[70:73], v[98:101], 0
	v_mfma_f32_32x32x16_bf16 v[66:81], v[66:69], v[98:101], 0
	s_waitcnt lgkmcnt(5)
	v_mfma_f32_32x32x16_bf16 v[82:97], v[114:117], v[102:105], v[82:97]
	s_waitcnt lgkmcnt(4)
	v_mfma_f32_32x32x16_bf16 v[66:81], v[118:121], v[102:105], v[66:81]
	s_waitcnt lgkmcnt(3)
	v_mfma_f32_32x32x16_bf16 v[82:97], v[122:125], v[106:109], v[82:97]
	s_waitcnt lgkmcnt(2)
	v_mfma_f32_32x32x16_bf16 v[66:81], v[126:129], v[106:109], v[66:81]
	s_waitcnt lgkmcnt(1)
	v_mfma_f32_32x32x16_bf16 v[82:97], v[138:141], v[110:113], v[82:97]
	s_waitcnt lgkmcnt(0)
	v_mfma_f32_32x32x16_bf16 v[66:81], v[142:145], v[110:113], v[66:81]
	s_and_saveexec_b64 s[0:1], s[40:41]
	s_cbranch_execz .LBB0_488
	s_sub_i32 s3, 0, s3
	v_add3_u32 v0, s3, v148, v153
	s_movk_i32 s4, 0xffc0
	s_movk_i32 s3, 0xffe0
	v_add_u32_e32 v100, -1, v0
	v_med3_i32 v101, v100, s4, v214
	v_med3_i32 v100, v100, s3, v215
	v_lshl_add_u32 v102, v100, 2, s33
	v_add_u32_e32 v100, -2, v0
	v_med3_i32 v103, v100, s4, v214
	v_med3_i32 v100, v100, s3, v215
	v_lshl_add_u32 v104, v100, 2, s33
	v_add_u32_e32 v100, -3, v0
	v_med3_i32 v98, v0, s4, v214
	v_med3_i32 v99, v0, s3, v215
	v_med3_i32 v105, v100, s4, v214
	v_med3_i32 v100, v100, s3, v215
	v_lshl_add_u32 v98, v98, 2, s33
	v_lshl_add_u32 v99, v99, 2, s33
	v_lshl_add_u32 v101, v101, 2, s33
	v_lshl_add_u32 v103, v103, 2, s33
	v_lshl_add_u32 v105, v105, 2, s33
	v_lshl_add_u32 v106, v100, 2, s33
	ds_read_b32 v98, v98 offset:256
	ds_read_b32 v100, v99 offset:128
	ds_read_b32 v99, v101 offset:256
	ds_read_b32 v101, v102 offset:128
	ds_read_b32 v102, v103 offset:256
	ds_read_b32 v104, v104 offset:128
	ds_read_b32 v103, v105 offset:256
	ds_read_b32 v105, v106 offset:128
	v_add_u32_e32 v106, -8, v0
	v_med3_i32 v107, v106, s4, v214
	v_med3_i32 v106, v106, s3, v215
	v_lshl_add_u32 v108, v106, 2, s33
	v_add_u32_e32 v106, -9, v0
	v_med3_i32 v109, v106, s4, v214
	v_med3_i32 v106, v106, s3, v215
	v_lshl_add_u32 v110, v106, 2, s33
	v_add_u32_e32 v106, -10, v0
	v_med3_i32 v111, v106, s4, v214
	v_med3_i32 v106, v106, s3, v215
	v_lshl_add_u32 v112, v106, 2, s33
	v_add_u32_e32 v106, -11, v0
	v_med3_i32 v113, v106, s4, v214
	v_med3_i32 v106, v106, s3, v215
	v_lshl_add_u32 v107, v107, 2, s33
	v_lshl_add_u32 v109, v109, 2, s33
	v_lshl_add_u32 v111, v111, 2, s33
	v_lshl_add_u32 v113, v113, 2, s33
	v_lshl_add_u32 v114, v106, 2, s33
	ds_read_b32 v106, v107 offset:256
	ds_read_b32 v108, v108 offset:128
	ds_read_b32 v107, v109 offset:256
	ds_read_b32 v109, v110 offset:128
	ds_read_b32 v110, v111 offset:256
	ds_read_b32 v112, v112 offset:128
	ds_read_b32 v111, v113 offset:256
	ds_read_b32 v113, v114 offset:128
	v_add_u32_e32 v114, -16, v0
	v_med3_i32 v115, v114, s4, v214
	v_med3_i32 v114, v114, s3, v215
	v_lshl_add_u32 v116, v114, 2, s33
	v_subrev_u32_e32 v114, 17, v0
	v_med3_i32 v117, v114, s4, v214
	v_med3_i32 v114, v114, s3, v215
	v_lshl_add_u32 v118, v114, 2, s33
	v_subrev_u32_e32 v114, 18, v0
	v_med3_i32 v119, v114, s4, v214
	v_med3_i32 v114, v114, s3, v215
	v_lshl_add_u32 v120, v114, 2, s33
	v_subrev_u32_e32 v114, 19, v0
	v_med3_i32 v121, v114, s4, v214
	v_med3_i32 v114, v114, s3, v215
	v_lshl_add_u32 v115, v115, 2, s33
	v_lshl_add_u32 v117, v117, 2, s33
	v_lshl_add_u32 v119, v119, 2, s33
	v_lshl_add_u32 v121, v121, 2, s33
	v_lshl_add_u32 v122, v114, 2, s33
	ds_read_b32 v114, v115 offset:256
	ds_read_b32 v116, v116 offset:128
	ds_read_b32 v115, v117 offset:256
	ds_read_b32 v117, v118 offset:128
	ds_read_b32 v118, v119 offset:256
	ds_read_b32 v120, v120 offset:128
	ds_read_b32 v119, v121 offset:256
	ds_read_b32 v121, v122 offset:128
	v_subrev_u32_e32 v122, 24, v0
	v_med3_i32 v123, v122, s4, v214
	v_med3_i32 v122, v122, s3, v215
	v_lshl_add_u32 v124, v122, 2, s33
	v_subrev_u32_e32 v122, 25, v0
	v_med3_i32 v125, v122, s4, v214
	v_med3_i32 v122, v122, s3, v215
	v_lshl_add_u32 v136, v122, 2, s33
	v_subrev_u32_e32 v122, 26, v0
	v_med3_i32 v126, v122, s4, v214
	v_med3_i32 v122, v122, s3, v215
	v_subrev_u32_e32 v0, 27, v0
	v_lshl_add_u32 v128, v122, 2, s33
	v_med3_i32 v122, v0, s4, v214
	v_lshl_add_u32 v123, v123, 2, s33
	v_lshl_add_u32 v125, v125, 2, s33
	v_lshl_add_u32 v126, v126, 2, s33
	v_lshl_add_u32 v127, v122, 2, s33
	v_med3_i32 v0, v0, s3, v215
	v_lshl_add_u32 v0, v0, 2, s33
	ds_read_b32 v122, v123 offset:256
	ds_read_b32 v124, v124 offset:128
	ds_read_b32 v126, v126 offset:256
	ds_read_b32 v127, v127 offset:256
	ds_read_b32 v123, v125 offset:256
	ds_read_b32 v129, v0 offset:128
	ds_read_b32 v128, v128 offset:128
	ds_read_b32 v125, v136 offset:128
	s_waitcnt lgkmcnt(4)
	v_pk_add_f32 v[96:97], v[96:97], v[126:127]
	s_waitcnt lgkmcnt(3)
	v_pk_add_f32 v[94:95], v[94:95], v[122:123]
	v_pk_add_f32 v[92:93], v[92:93], v[118:119]
	v_pk_add_f32 v[90:91], v[90:91], v[114:115]
	v_pk_add_f32 v[88:89], v[88:89], v[110:111]
	v_pk_add_f32 v[86:87], v[86:87], v[106:107]
	v_pk_add_f32 v[84:85], v[84:85], v[102:103]
	v_pk_add_f32 v[82:83], v[82:83], v[98:99]
	s_waitcnt lgkmcnt(1)
	v_pk_add_f32 v[80:81], v[80:81], v[128:129]
	s_waitcnt lgkmcnt(0)
	v_pk_add_f32 v[78:79], v[78:79], v[124:125]
	v_pk_add_f32 v[76:77], v[76:77], v[120:121]
	v_pk_add_f32 v[74:75], v[74:75], v[116:117]
	v_pk_add_f32 v[72:73], v[72:73], v[112:113]
	v_pk_add_f32 v[70:71], v[70:71], v[108:109]
	v_pk_add_f32 v[68:69], v[68:69], v[104:105]
	v_pk_add_f32 v[66:67], v[66:67], v[100:101]

.LBB0_490:
	v_sub_f32_e32 v0, v150, v0
	v_pk_add_f32 v[82:83], v[82:83], v[0:1] op_sel_hi:[1,0] neg_lo:[0,1] neg_hi:[0,1]
	v_pk_add_f32 v[66:67], v[66:67], v[0:1] op_sel_hi:[1,0] neg_lo:[0,1] neg_hi:[0,1]
	v_exp_f32_e32 v82, v82
	v_exp_f32_e32 v83, v83
	v_exp_f32_e32 v98, v66
	v_exp_f32_e32 v99, v67
	v_pk_add_f32 v[66:67], v[84:85], v[0:1] op_sel_hi:[1,0] neg_lo:[0,1] neg_hi:[0,1]
	v_pk_add_f32 v[68:69], v[68:69], v[0:1] op_sel_hi:[1,0] neg_lo:[0,1] neg_hi:[0,1]
	v_exp_f32_e32 v84, v66
	v_exp_f32_e32 v85, v67
	v_exp_f32_e32 v100, v68
	v_exp_f32_e32 v101, v69
	v_pk_add_f32 v[68:69], v[86:87], v[0:1] op_sel_hi:[1,0] neg_lo:[0,1] neg_hi:[0,1]
	v_pk_add_f32 v[66:67], v[82:83], 0 op_sel_hi:[1,0]
	v_pk_add_f32 v[70:71], v[70:71], v[0:1] op_sel_hi:[1,0] neg_lo:[0,1] neg_hi:[0,1]
	v_exp_f32_e32 v68, v68
	v_exp_f32_e32 v69, v69
	v_pk_add_f32 v[66:67], v[98:99], v[66:67]
	v_exp_f32_e32 v86, v70
	v_exp_f32_e32 v87, v71
	v_pk_add_f32 v[70:71], v[88:89], v[0:1] op_sel_hi:[1,0] neg_lo:[0,1] neg_hi:[0,1]
	v_pk_add_f32 v[66:67], v[84:85], v[66:67]
	v_pk_add_f32 v[72:73], v[72:73], v[0:1] op_sel_hi:[1,0] neg_lo:[0,1] neg_hi:[0,1]
	v_exp_f32_e32 v70, v70
	v_exp_f32_e32 v71, v71
	v_pk_add_f32 v[66:67], v[100:101], v[66:67]
	v_exp_f32_e32 v88, v72
	v_exp_f32_e32 v89, v73
	v_pk_add_f32 v[72:73], v[90:91], v[0:1] op_sel_hi:[1,0] neg_lo:[0,1] neg_hi:[0,1]
	v_pk_add_f32 v[66:67], v[68:69], v[66:67]
	v_pk_add_f32 v[74:75], v[74:75], v[0:1] op_sel_hi:[1,0] neg_lo:[0,1] neg_hi:[0,1]
	v_exp_f32_e32 v72, v72
	v_exp_f32_e32 v73, v73
	v_pk_add_f32 v[66:67], v[86:87], v[66:67]
	v_exp_f32_e32 v90, v74
	v_exp_f32_e32 v91, v75
	v_pk_add_f32 v[74:75], v[92:93], v[0:1] op_sel_hi:[1,0] neg_lo:[0,1] neg_hi:[0,1]
	v_pk_add_f32 v[66:67], v[70:71], v[66:67]
	v_pk_add_f32 v[76:77], v[76:77], v[0:1] op_sel_hi:[1,0] neg_lo:[0,1] neg_hi:[0,1]
	v_exp_f32_e32 v74, v74
	v_exp_f32_e32 v75, v75
	v_pk_add_f32 v[66:67], v[88:89], v[66:67]
	v_exp_f32_e32 v92, v76
	v_exp_f32_e32 v93, v77
	v_pk_add_f32 v[76:77], v[94:95], v[0:1] op_sel_hi:[1,0] neg_lo:[0,1] neg_hi:[0,1]
	v_pk_add_f32 v[66:67], v[72:73], v[66:67]
	v_pk_add_f32 v[78:79], v[78:79], v[0:1] op_sel_hi:[1,0] neg_lo:[0,1] neg_hi:[0,1]
	v_exp_f32_e32 v76, v76
	v_exp_f32_e32 v77, v77
	v_pk_add_f32 v[66:67], v[90:91], v[66:67]
	v_exp_f32_e32 v94, v78
	v_exp_f32_e32 v95, v79
	v_pk_add_f32 v[78:79], v[96:97], v[0:1] op_sel_hi:[1,0] neg_lo:[0,1] neg_hi:[0,1]
	v_pk_add_f32 v[66:67], v[74:75], v[66:67]
	v_pk_add_f32 v[80:81], v[80:81], v[0:1] op_sel_hi:[1,0] neg_lo:[0,1] neg_hi:[0,1]
	v_exp_f32_e32 v78, v78
	v_exp_f32_e32 v79, v79
	v_pk_add_f32 v[66:67], v[92:93], v[66:67]
	v_exp_f32_e32 v96, v80
	v_exp_f32_e32 v97, v81
	v_pk_add_f32 v[66:67], v[76:77], v[66:67]
	v_cvt_pk_bf16_f32 v68, v68, v69
	v_cvt_pk_bf16_f32 v69, v70, v71
	v_cvt_pk_bf16_f32 v70, v72, v73
	v_cvt_pk_bf16_f32 v71, v74, v75
	v_cvt_pk_bf16_f32 v72, v76, v77
	s_nop 0
	v_pk_add_f32 v[66:67], v[94:95], v[66:67]
	v_cvt_pk_bf16_f32 v73, v78, v79
	v_cvt_pk_bf16_f32 v74, v98, v99
	v_cvt_pk_bf16_f32 v75, v100, v101
	v_cvt_pk_bf16_f32 v76, v86, v87
	v_cvt_pk_bf16_f32 v77, v88, v89
	s_nop 0
	v_pk_add_f32 v[66:67], v[78:79], v[66:67]
	v_cvt_pk_bf16_f32 v78, v90, v91
	v_cvt_pk_bf16_f32 v79, v92, v93
	v_cvt_pk_bf16_f32 v80, v94, v95
	v_cvt_pk_bf16_f32 v81, v96, v97
	v_add3_u32 v0, s2, v133, v130
	v_pk_add_f32 v[102:103], v[96:97], v[66:67]
	v_cvt_pk_bf16_f32 v66, v82, v83
	v_cvt_pk_bf16_f32 v67, v84, v85
	ds_read_b128 v[82:85], v0 offset:22016
	ds_read_b128 v[86:89], v0 offset:26624
	ds_read_b128 v[90:93], v0 offset:31232
	ds_read_b128 v[94:97], v0 offset:17408
	v_add_f32_e32 v114, v102, v103
	ds_read_b128 v[98:101], v0 offset:17440
	ds_read_b128 v[102:105], v0 offset:22048
	ds_read_b128 v[106:109], v0 offset:26656
	ds_read_b128 v[110:113], v0 offset:31264
	s_waitcnt lgkmcnt(4)
	v_mfma_f32_32x32x16_bf16 v[50:65], v[94:97], v[66:69], v[50:65]
	v_add_f32_e32 v131, v131, v114
	v_mfma_f32_32x32x16_bf16 v[34:49], v[82:85], v[66:69], v[34:49]
	v_mfma_f32_32x32x16_bf16 v[18:33], v[86:89], v[66:69], v[18:33]
	v_mfma_f32_32x32x16_bf16 v[2:17], v[90:93], v[66:69], v[2:17]
	ds_read_b128 v[66:69], v0 offset:17472
	ds_read_b128 v[82:85], v0 offset:22080
	ds_read_b128 v[86:89], v0 offset:26688
	ds_read_b128 v[90:93], v0 offset:31296
	s_waitcnt lgkmcnt(7)
	v_mfma_f32_32x32x16_bf16 v[50:65], v[98:101], v[70:73], v[50:65]
	s_waitcnt lgkmcnt(6)
	v_mfma_f32_32x32x16_bf16 v[34:49], v[102:105], v[70:73], v[34:49]
	s_waitcnt lgkmcnt(5)
	v_mfma_f32_32x32x16_bf16 v[18:33], v[106:109], v[70:73], v[18:33]
	s_waitcnt lgkmcnt(4)
	v_mfma_f32_32x32x16_bf16 v[2:17], v[110:113], v[70:73], v[2:17]
	ds_read_b128 v[70:73], v0 offset:17504
	ds_read_b128 v[94:97], v0 offset:22112
	ds_read_b128 v[98:101], v0 offset:26720
	ds_read_b128 v[102:105], v0 offset:31328
	s_waitcnt lgkmcnt(7)
	v_mfma_f32_32x32x16_bf16 v[50:65], v[66:69], v[74:77], v[50:65]
	s_waitcnt lgkmcnt(6)
	v_mfma_f32_32x32x16_bf16 v[34:49], v[82:85], v[74:77], v[34:49]
	s_waitcnt lgkmcnt(5)
	v_mfma_f32_32x32x16_bf16 v[18:33], v[86:89], v[74:77], v[18:33]
	s_waitcnt lgkmcnt(4)
	v_mfma_f32_32x32x16_bf16 v[2:17], v[90:93], v[74:77], v[2:17]
	s_waitcnt lgkmcnt(3)
	v_mfma_f32_32x32x16_bf16 v[50:65], v[70:73], v[78:81], v[50:65]
	s_waitcnt lgkmcnt(2)
	v_mfma_f32_32x32x16_bf16 v[34:49], v[94:97], v[78:81], v[34:49]
	s_waitcnt lgkmcnt(1)
	v_mfma_f32_32x32x16_bf16 v[18:33], v[98:101], v[78:81], v[18:33]
	s_waitcnt lgkmcnt(0)
	v_mfma_f32_32x32x16_bf16 v[2:17], v[102:105], v[78:81], v[2:17]
.LBB0_491:
	s_setprio 0
	s_or_b64 exec, exec, s[62:63]
	s_barrier
